# x f32->bf16 copy: non-temporal hint on the x loads (streamed once)
# baseline (speedup 1.0000x reference)
; DI unsigned pk2(float lo, float hi) { const f32x2 v = {lo, hi}; const hwbf16x2 b = __builtin_convertvector(v, hwbf16x2); return __builtin_bit_cast(unsigned, b); }
; __global__ void __launch_bounds__(512, 2) hybrid_fwd(Args unused_args) {
;     ...
; #pragma unroll 4
;       for (size_t i = (size_t)bid * 512 + tid; i < (size_t)T * DMODEL / 8; i += (size_t)G * 512) { const f32x4 v0 = ((const f32x4*)x)[2 * i], v1 = ((const f32x4*)x)[2 * i + 1];
;           u32x4 w; w.x = pk2(v0[0], v0[1]); w.y = pk2(v0[2], v0[3]); w.z = pk2(v1[0], v1[1]); w.w = pk2(v1[2], v1[3]); ((u32x4*)XB)[i] = w; }
.Lmy_xconv_loop:
	global_load_dwordx4 v[16:19], v9, s[2:3] nt
	global_load_dwordx4 v[20:23], v9, s[2:3] offset:16 nt
	s_add_u32 s2, s2, 0x800
	s_addc_u32 s3, s3, 0
	global_load_dwordx4 v[24:27], v9, s[2:3] nt
	global_load_dwordx4 v[28:31], v9, s[2:3] offset:16 nt
	s_add_u32 s2, s2, 0x800
	s_addc_u32 s3, s3, 0
	global_load_dwordx4 v[32:35], v9, s[2:3] nt
	global_load_dwordx4 v[36:39], v9, s[2:3] offset:16 nt
	s_add_u32 s2, s2, 0x800
	s_addc_u32 s3, s3, 0
	global_load_dwordx4 v[40:43], v9, s[2:3] nt
	global_load_dwordx4 v[44:47], v9, s[2:3] offset:16 nt
	s_add_u32 s2, s2, 0x800
	s_addc_u32 s3, s3, 0
	global_load_dwordx4 v[48:51], v9, s[2:3] nt
	global_load_dwordx4 v[52:55], v9, s[2:3] offset:16 nt
	s_add_u32 s2, s2, 0x800
	s_addc_u32 s3, s3, 0
	global_load_dwordx4 v[56:59], v9, s[2:3] nt
	global_load_dwordx4 v[60:63], v9, s[2:3] offset:16 nt
	s_add_u32 s2, s2, 0x800
	s_addc_u32 s3, s3, 0
	global_load_dwordx4 v[64:67], v9, s[2:3] nt
	global_load_dwordx4 v[68:71], v9, s[2:3] offset:16 nt
	s_add_u32 s2, s2, 0x800
	s_addc_u32 s3, s3, 0
	global_load_dwordx4 v[72:75], v9, s[2:3] nt
	global_load_dwordx4 v[76:79], v9, s[2:3] offset:16 nt
	s_add_u32 s2, s2, 0x1ffc800
	s_addc_u32 s3, s3, 0
	s_waitcnt vmcnt(14)
	v_cvt_pk_bf16_f32 v16, v16, v17
	v_cvt_pk_bf16_f32 v17, v18, v19
	v_cvt_pk_bf16_f32 v18, v20, v21
	v_cvt_pk_bf16_f32 v19, v22, v23
	global_store_dwordx4 v10, v[16:19], s[6:7]
	s_add_u32 s6, s6, 0x400
	s_addc_u32 s7, s7, 0
	s_waitcnt vmcnt(13)
	v_cvt_pk_bf16_f32 v24, v24, v25
	v_cvt_pk_bf16_f32 v25, v26, v27
	v_cvt_pk_bf16_f32 v26, v28, v29
	v_cvt_pk_bf16_f32 v27, v30, v31
	global_store_dwordx4 v10, v[24:27], s[6:7]
	s_add_u32 s6, s6, 0x400
	s_addc_u32 s7, s7, 0
	s_waitcnt vmcnt(12)
	v_cvt_pk_bf16_f32 v32, v32, v33
	v_cvt_pk_bf16_f32 v33, v34, v35
	v_cvt_pk_bf16_f32 v34, v36, v37
	v_cvt_pk_bf16_f32 v35, v38, v39
	global_store_dwordx4 v10, v[32:35], s[6:7]
	s_add_u32 s6, s6, 0x400
	s_addc_u32 s7, s7, 0
	s_waitcnt vmcnt(11)
	v_cvt_pk_bf16_f32 v40, v40, v41
	v_cvt_pk_bf16_f32 v41, v42, v43
	v_cvt_pk_bf16_f32 v42, v44, v45
	v_cvt_pk_bf16_f32 v43, v46, v47
	global_store_dwordx4 v10, v[40:43], s[6:7]
	s_add_u32 s6, s6, 0x400
	s_addc_u32 s7, s7, 0
	s_waitcnt vmcnt(10)
	v_cvt_pk_bf16_f32 v48, v48, v49
	v_cvt_pk_bf16_f32 v49, v50, v51
	v_cvt_pk_bf16_f32 v50, v52, v53
	v_cvt_pk_bf16_f32 v51, v54, v55
	global_store_dwordx4 v10, v[48:51], s[6:7]
	s_add_u32 s6, s6, 0x400
	s_addc_u32 s7, s7, 0
	s_waitcnt vmcnt(9)
	v_cvt_pk_bf16_f32 v56, v56, v57
	v_cvt_pk_bf16_f32 v57, v58, v59
	v_cvt_pk_bf16_f32 v58, v60, v61
	v_cvt_pk_bf16_f32 v59, v62, v63
	global_store_dwordx4 v10, v[56:59], s[6:7]
	s_add_u32 s6, s6, 0x400
	s_addc_u32 s7, s7, 0
	s_waitcnt vmcnt(8)
	v_cvt_pk_bf16_f32 v64, v64, v65
	v_cvt_pk_bf16_f32 v65, v66, v67
	v_cvt_pk_bf16_f32 v66, v68, v69
	v_cvt_pk_bf16_f32 v67, v70, v71
	global_store_dwordx4 v10, v[64:67], s[6:7]
	s_add_u32 s6, s6, 0x400
	s_addc_u32 s7, s7, 0
	s_waitcnt vmcnt(7)
	v_cvt_pk_bf16_f32 v72, v72, v73
	v_cvt_pk_bf16_f32 v73, v74, v75
	v_cvt_pk_bf16_f32 v74, v76, v77
	v_cvt_pk_bf16_f32 v75, v78, v79
	global_store_dwordx4 v10, v[72:75], s[6:7]
	s_add_u32 s6, s6, 0xffe400
	s_addc_u32 s7, s7, 0
	s_add_i32 s8, s8, -1
	s_cmp_lg_u32 s8, 0
	s_cbranch_scc1 .Lmy_xconv_loop
	s_branch .Lmy_xconv_done
